# SB loop: hoisted Q-load wait out of the tile loop so next-tile prefetch stays in flight; Wo layer0 residual epilogue loads batched 8 at a time
# speedup vs baseline: 1.0077x; 1.0021x over previous
; #define LAS __attribute__((address_space(3)))
; DEV void sb_pass(LAS unsigned char* lds, int tid, int r, int h, int w, const bf16* Kp, size_t kpitch, const bf16* VTp, size_t vpitch, int t_hi, const bf16x8 (&qf)[4], int hi_lim, f32x16 (&o)[2]) {
;     TileRegs R; float Rr = 0.f; const int lane = tid & 63;
;     LAS unsigned* flags = (LAS unsigned*)(lds + AL_FLAGS);
;     tile_load<64>(R, Kp, kpitch, nullptr, VTp, vpitch, 64 * t_hi, tid, true);
;     tile_store<64>(R, lds + AL_K0, lds + AL_V0, tid, true);
;     __syncthreads();
;     const int nt = t_hi + 1;
; template <int LAYER> DEV void attn_mha_phase(LAS unsigned char* lds, unsigned char* ws, int tid, int G, int c) {
;     ...
;             const bf16* qrow = (const bf16*)(S + S_QK) + token * 2048 + hh * 64;
; #pragma unroll
;             for (int s = 0; s < 4; ++s) qf[s] = *(const bf16x8*)(qrow + 16 * s + 8 * h);
.LBB0_177:
	s_bitcmp0_b32 s41, 0
	s_cselect_b32 s10, s93, s92
	s_lshl_b32 s12, s10, 8
	v_add_u32_e32 v102, s12, v95
	v_ashrrev_i32_e32 v103, 31, v102
	v_lshl_add_u64 v[104:105], v[102:103], 0, s[86:87]
	s_add_i32 s6, s41, s97
	v_lshlrev_b64 v[0:1], 12, v[104:105]
	v_lshl_add_u64 v[0:1], s[20:21], 0, v[0:1]
	s_lshl_b32 s26, s6, 6
	s_lshl_b32 s6, s6, 7
	s_mov_b32 s7, s27
	v_lshl_add_u64 v[0:1], v[0:1], 0, s[6:7]
	s_add_u32 s6, s14, s6
	s_addc_u32 s7, s15, 0
	s_lshl_b32 s10, s10, 2
	s_or_b32 s42, s10, 3
	s_lshl_b32 s10, s42, 6
	v_add_u32_e32 v2, s10, v90
	v_ashrrev_i32_e32 v3, 31, v2
	s_lshl_b64 s[8:9], s[26:27], 16
	v_lshlrev_b64 v[2:3], 12, v[2:3]
	v_lshl_add_u64 v[2:3], s[6:7], 0, v[2:3]
	v_lshl_add_u64 v[32:33], v[92:93], 0, s[8:9]
	s_ashr_i32 s11, s10, 31
	v_lshl_add_u64 v[2:3], v[2:3], 0, v[98:99]
	v_lshl_add_u64 v[4:5], s[10:11], 1, v[32:33]
	v_lshl_add_u64 v[0:1], v[0:1], 0, v[96:97]
	v_lshl_add_u64 v[4:5], v[4:5], 0, v[98:99]
	global_load_dwordx4 v[80:83], v[2:3], off offset:2048
	global_load_dwordx4 v[84:87], v[4:5], off
	global_load_dwordx4 v[64:67], v[0:1], off
	global_load_dwordx4 v[68:71], v[0:1], off offset:32
	global_load_dwordx4 v[72:75], v[0:1], off offset:64
	global_load_dwordx4 v[76:79], v[0:1], off offset:96
	s_max_i32 s44, s42, -1
	s_mov_b32 s43, s27
	v_mov_b32_e32 v103, v88
	v_mov_b32_e32 v16, v88
	v_mov_b32_e32 v17, v88
	v_mov_b32_e32 v18, v88
	v_mov_b32_e32 v19, v88
	v_mov_b32_e32 v20, v88
	v_mov_b32_e32 v21, v88
	v_mov_b32_e32 v22, v88
	v_mov_b32_e32 v23, v88
	v_mov_b32_e32 v24, v88
	v_mov_b32_e32 v25, v88
	v_mov_b32_e32 v26, v88
	v_mov_b32_e32 v27, v88
	v_mov_b32_e32 v28, v88
	v_mov_b32_e32 v29, v88
	v_mov_b32_e32 v30, v88
	v_mov_b32_e32 v31, v88
	v_mov_b32_e32 v0, v88
	v_mov_b32_e32 v1, v88
	v_mov_b32_e32 v2, v88
	v_mov_b32_e32 v3, v88
	v_mov_b32_e32 v4, v88
	v_mov_b32_e32 v5, v88
	v_mov_b32_e32 v6, v88
	v_mov_b32_e32 v7, v88
	v_mov_b32_e32 v8, v88
	v_mov_b32_e32 v9, v88
	v_mov_b32_e32 v10, v88
	v_mov_b32_e32 v11, v88
	v_mov_b32_e32 v12, v88
	v_mov_b32_e32 v13, v88
	v_mov_b32_e32 v14, v88
	v_add_u32_e32 v101, -1, v102
	v_mov_b32_e32 v91, v102
	s_or_b32 s34, s12, 0x80
	v_lshl_add_u64 v[106:107], s[6:7], 0, v[98:99]
	v_lshl_add_u64 v[108:109], v[32:33], 0, v[98:99]
	s_add_i32 s44, s44, 1
	v_mov_b32_e32 v15, v88
	s_waitcnt vmcnt(5)
	ds_write_b128 v132, v[80:83]
	s_waitcnt vmcnt(4)
	ds_write2_b64 v143, v[84:85], v[86:87] offset1:1
	s_waitcnt vmcnt(0) lgkmcnt(0)
	s_barrier
	s_branch .LBB0_179

; #define LAS __attribute__((address_space(3)))
; DEV float shx(float v, int m, int lane) { return __builtin_bit_cast(float, __builtin_amdgcn_ds_bpermute((lane ^ m) << 2, __builtin_bit_cast(int, v))); }
; DEV float fexp2(float x) { return __builtin_amdgcn_exp2f(x); }
; DEV float flog2(float x) { return __builtin_amdgcn_logf(x); }
; DEV void sb_pass(LAS unsigned char* lds, int tid, int r, int h, int w, const bf16* Kp, size_t kpitch, const bf16* VTp, size_t vpitch, int t_hi, const bf16x8 (&qf)[4], int hi_lim, f32x16 (&o)[2]) {
;     ...
;     for (int it = 0; it < nt; ++it) {
;         const int t = t_hi - it, par = it & 1;
;         LAS unsigned char* kb = lds + (par ? AL_K1 : AL_K0); LAS unsigned char* vb = lds + (par ? AL_V1 : AL_V0);
;         if (it + 1 < nt) tile_load<64>(R, Kp, kpitch, nullptr, VTp, vpitch, 64 * (t - 1), tid, true);
;         const int k0 = 64 * t;
;         if (__any((k0 <= hi_lim) ? 1 : 0)) {
;             f32x16 st[2];
;             qk_tile<64>(st, kb, qf, r, h);
;             f32x16 spv[2]; float G[8], Gp[8];
; #pragma unroll
;             for (int b2 = 0; b2 < 2; ++b2)
; #pragma unroll
;                 for (int g = 0; g < 4; ++g) {
;                     float gs = 0.f;
; #pragma unroll
;                     for (int i = 0; i < 4; ++i) { const int key = k0 + 32 * b2 + 8 * g + 4 * h + i; const bool vis = key <= hi_lim;
;                         const float z = st[b2][4 * g + i] * 0.125f; const float e = fexp2(-fabsf(z) * LOG2E); const float s = vis ? (fmaxf(z, 0.f) + LN2 * flog2(1.f + e)) : 0.f;
;                         spv[b2][4 * g + i] = s; st[b2][4 * g + i] = vis ? (z - s) : -1e30f; gs += s; }
;                     G[4 * b2 + g] = gs;
;                 }
; #pragma unroll
;             for (int o8 = 0; o8 < 8; ++o8) Gp[o8] = shx(G[o8], 32, lane);
.LBB0_182:
	s_and_b32 s35, s43, 1
	s_cmp_eq_u32 s35, 0
	s_cselect_b64 s[38:39], -1, 0
	s_add_i32 s6, s34, 64
	v_cmp_lt_i32_e32 vcc, s6, v102
	s_cbranch_vccz .LBB0_184
	s_and_b64 s[6:7], s[38:39], exec
	s_cselect_b32 s6, 0, 0x3400
	v_add_u32_e32 v36, s6, v135
	ds_read_b128 v[32:35], v36
	ds_read_b128 v[48:51], v36 offset:32
	ds_read_b128 v[52:55], v36 offset:64
	ds_read_b128 v[56:59], v36 offset:96
	ds_read_b128 v[60:63], v36 offset:4608
	ds_read_b128 v[110:113], v36 offset:4640
	ds_read_b128 v[114:117], v36 offset:4672
	ds_read_b128 v[118:121], v36 offset:4704
	s_cselect_b32 s45, 0x13800, s29
	s_setprio 1
	s_waitcnt lgkmcnt(7)
	v_mfma_f32_32x32x16_bf16 v[32:47], v[32:35], v[64:67], 0
	s_waitcnt lgkmcnt(6)
	v_mfma_f32_32x32x16_bf16 v[32:47], v[48:51], v[68:71], v[32:47]
	s_waitcnt lgkmcnt(5)
	v_mfma_f32_32x32x16_bf16 v[32:47], v[52:55], v[72:75], v[32:47]
	s_waitcnt lgkmcnt(4)
	v_mfma_f32_32x32x16_bf16 v[32:47], v[56:59], v[76:79], v[32:47]
	s_waitcnt lgkmcnt(3)
	v_mfma_f32_32x32x16_bf16 v[48:63], v[60:63], v[64:67], 0
	s_waitcnt lgkmcnt(2)
	v_mfma_f32_32x32x16_bf16 v[48:63], v[110:113], v[68:71], v[48:63]
	s_waitcnt lgkmcnt(1)
	v_mfma_f32_32x32x16_bf16 v[48:63], v[114:117], v[72:75], v[48:63]
	s_waitcnt lgkmcnt(0)
	v_mfma_f32_32x32x16_bf16 v[48:63], v[118:121], v[76:79], v[48:63]
	s_setprio 0
	s_nop 3
	v_mul_f32_e32 v89, 0x3e000000, v38
	v_mul_f32_e64 v110, |v89|, s31
	v_exp_f32_e32 v110, v110
	v_mul_f32_e32 v112, 0x3e000000, v46
	v_mul_f32_e64 v114, |v112|, s31
	v_exp_f32_e32 v114, v114
	v_add_f32_e32 v110, 1.0, v110
	v_log_f32_e32 v110, v110
	v_mul_f32_e32 v111, 0x3e000000, v39
	v_mul_f32_e64 v113, |v111|, s31
	v_max_f32_e32 v115, 0, v111
	v_mul_f32_e32 v152, 0x3f317218, v110
	v_exp_f32_e32 v110, v113
	v_add_f32_e32 v111, 1.0, v114
	v_log_f32_e32 v111, v111
	v_max_f32_e32 v123, 0, v112
	v_add_f32_e32 v110, 1.0, v110
	v_log_f32_e32 v117, v110
	v_mul_f32_e32 v110, 0x3e000000, v47
	v_mul_f32_e32 v114, 0x3f317218, v111
	v_mul_f32_e64 v111, |v110|, s31
	v_mul_f32_e32 v112, 0x3e000000, v54
	v_exp_f32_e32 v111, v111
	v_mul_f32_e64 v113, |v112|, s31
	v_exp_f32_e32 v113, v113
	v_max_f32_e32 v125, 0, v110
	v_add_f32_e32 v110, 1.0, v111
	v_mul_f32_e32 v111, 0x3e000000, v55
	v_log_f32_e32 v127, v110
	v_add_f32_e32 v110, 1.0, v113
	v_mul_f32_e64 v113, |v111|, s31
	v_log_f32_e32 v110, v110
	v_exp_f32_e32 v113, v113
	v_max_f32_e32 v129, 0, v111
	v_max_f32_e32 v121, 0, v112
	v_mul_f32_e32 v116, 0x3f317218, v110
	v_add_f32_e32 v110, 1.0, v113
	v_log_f32_e32 v131, v110
	v_mul_f32_e32 v110, 0x3e000000, v56
	v_mul_f32_e64 v111, |v110|, s31
	v_exp_f32_e32 v111, v111
	v_mul_f32_e32 v112, 0x3e000000, v57
	v_mul_f32_e64 v113, |v112|, s31
	v_exp_f32_e32 v113, v113
	v_add_f32_e32 v111, 1.0, v111
	v_log_f32_e32 v118, v111
	v_max_f32_e32 v111, 0, v110
	v_add_f32_e32 v110, 1.0, v113
	v_log_f32_e32 v110, v110
	v_fmac_f32_e32 v111, 0x3f317218, v118
	v_fma_f32 v120, v56, s28, -v111
	v_mul_f32_e32 v56, 0x3e000000, v58
	v_mul_f32_e32 v119, 0x3f317218, v110
	v_mul_f32_e64 v110, |v56|, s31
	v_max_f32_e32 v149, 0, v56
	v_mul_f32_e32 v56, 0x3e000000, v59
	v_max_f32_e32 v113, 0, v112
	v_mul_f32_e64 v112, |v56|, s31
	v_exp_f32_e32 v112, v112
	v_exp_f32_e32 v110, v110
	v_max_f32_e32 v159, 0, v56
	v_max_f32_e32 v89, 0, v89
	v_add_f32_e32 v56, 1.0, v112
	v_add_f32_e32 v110, 1.0, v110
	v_log_f32_e32 v161, v56
	v_mul_f32_e32 v56, 0x3e000000, v60
	v_mul_f32_e32 v112, 0x3e000000, v61
	v_log_f32_e32 v151, v110
	v_mul_f32_e64 v110, |v56|, s31
	v_mul_f32_e64 v118, |v112|, s31
	v_exp_f32_e32 v110, v110
	v_exp_f32_e32 v122, v118
	v_max_f32_e32 v118, 0, v56
	v_add_f32_e32 v110, 1.0, v110
	v_add_f32_e32 v56, 1.0, v122
	v_log_f32_e32 v110, v110
	v_log_f32_e32 v122, v56
	v_max_f32_e32 v56, 0, v112
	v_mul_f32_e32 v112, 0x3e000000, v62
	v_fmac_f32_e32 v118, 0x3f317218, v110
	v_mul_f32_e32 v110, 0x3f317218, v122
	v_mul_f32_e64 v122, |v112|, s31
	v_max_f32_e32 v148, 0, v112
	v_mul_f32_e32 v112, 0x3e000000, v63
	v_mul_f32_e64 v124, |v112|, s31
	v_exp_f32_e32 v124, v124
	v_exp_f32_e32 v122, v122
	v_max_f32_e32 v158, 0, v112
	v_fma_f32 v60, v60, s28, -v118
	v_add_f32_e32 v112, 1.0, v124
	v_log_f32_e32 v160, v112
	v_add_u32_e32 v112, s34, v94
	v_add_u32_e32 v157, 64, v112
	v_add_u32_e32 v154, 0x4a, v112
	v_add_u32_e32 v153, 0x43, v112
	v_add_u32_e32 v166, 0x51, v112
	v_add_u32_e32 v167, 0x53, v112
	v_add_u32_e32 v124, 0x61, v112
	v_add_u32_e32 v126, 0x63, v112
	v_mov_b32_e32 v112, v88
	v_add_f32_e32 v122, 1.0, v122
	v_pk_add_f32 v[112:113], v[112:113], v[118:119]
	v_log_f32_e32 v150, v122
	v_fma_f32 v122, v57, s28, -v113
	v_mov_b32_e32 v57, v88
	v_pk_add_f32 v[56:57], v[56:57], v[110:111]
	v_pk_fma_f32 v[118:119], v[150:151], s[30:31], v[148:149] op_sel_hi:[1,0,1]
	v_fma_f32 v128, v61, s28, -v56
	v_or_b32_e32 v61, 48, v157
	v_cmp_lt_i32_e32 vcc, v61, v91
	v_or_b32_e32 v61, 49, v157
	v_cmp_lt_i32_e64 s[6:7], v61, v91
	v_or_b32_e32 v61, 50, v157
	v_fma_f32 v58, v58, s28, -v119
	v_or_b32_e32 v110, 57, v157
	v_or_b32_e32 v111, 56, v157
	v_cmp_lt_i32_e64 s[8:9], v61, v91
	v_pk_fma_f32 v[158:159], v[160:161], s[30:31], v[158:159] op_sel_hi:[1,0,1]
	v_cndmask_b32_e32 v147, v144, v120, vcc
	v_or_b32_e32 v120, 58, v157
	v_cndmask_b32_e64 v149, v144, v58, s[8:9]
	v_or_b32_e32 v58, 51, v157
	v_cmp_lt_i32_e64 s[12:13], v111, v102
	v_cndmask_b32_e32 v57, 0, v57, vcc
	v_cmp_lt_i32_e32 vcc, v110, v102
	v_fma_f32 v59, v59, s28, -v159
	v_cndmask_b32_e64 v148, v144, v122, s[6:7]
	v_or_b32_e32 v122, 59, v157
	v_cmp_lt_i32_e64 s[10:11], v58, v91
	v_cndmask_b32_e64 v145, v144, v60, s[12:13]
	v_cndmask_b32_e64 v61, 0, v113, s[6:7]
	v_cndmask_b32_e64 v60, 0, v112, s[12:13]
	v_cndmask_b32_e32 v56, 0, v56, vcc
	v_cmp_lt_i32_e64 s[6:7], v120, v102
	v_cndmask_b32_e64 v150, v144, v59, s[10:11]
	v_pk_add_f32 v[110:111], v[60:61], v[56:57]
	v_cndmask_b32_e64 v59, 0, v119, s[8:9]
	v_cndmask_b32_e64 v58, 0, v118, s[6:7]
	v_cmp_lt_i32_e64 s[8:9], v122, v102
	v_pk_add_f32 v[112:113], v[58:59], v[110:111]
	v_cndmask_b32_e64 v111, 0, v159, s[10:11]
	v_cndmask_b32_e64 v110, 0, v158, s[8:9]
	v_fma_f32 v62, v62, s28, -v118
	v_pk_add_f32 v[118:119], v[110:111], v[112:113]
	ds_bpermute_b32 v113, v136, v119
	ds_bpermute_b32 v112, v136, v118
	v_fma_f32 v63, v63, s28, -v158
	v_cndmask_b32_e64 v60, v144, v62, s[6:7]
	v_cndmask_b32_e64 v151, v144, v63, s[8:9]
	v_cndmask_b32_e32 v57, v144, v128, vcc
	s_waitcnt lgkmcnt(0)
; DEV float shx(float v, int m, int lane) { return __builtin_bit_cast(float, __builtin_amdgcn_ds_bpermute((lane ^ m) << 2, __builtin_bit_cast(int, v))); }
; DEV float fexp2(float x) { return __builtin_amdgcn_exp2f(x); }
; DEV float flog2(float x) { return __builtin_amdgcn_logf(x); }
; DEV void sb_pass(LAS unsigned char* lds, int tid, int r, int h, int w, const bf16* Kp, size_t kpitch, const bf16* VTp, size_t vpitch, int t_hi, const bf16x8 (&qf)[4], int hi_lim, f32x16 (&o)[2]) {
;     ...
; #pragma unroll
;             for (int b2 = 0; b2 < 2; ++b2)
; #pragma unroll
;                 for (int g = 0; g < 4; ++g) {
;                     float gs = 0.f;
; #pragma unroll
;                     for (int i = 0; i < 4; ++i) { const int key = k0 + 32 * b2 + 8 * g + 4 * h + i; const bool vis = key <= hi_lim;
;                         const float z = st[b2][4 * g + i] * 0.125f; const float e = fexp2(-fabsf(z) * LOG2E); const float s = vis ? (fmaxf(z, 0.f) + LN2 * flog2(1.f + e)) : 0.f;
;                         spv[b2][4 * g + i] = s; st[b2][4 * g + i] = vis ? (z - s) : -1e30f; gs += s; }
;                     G[4 * b2 + g] = gs;
;                 }
; #pragma unroll
;             for (int o8 = 0; o8 < 8; ++o8) Gp[o8] = shx(G[o8], 32, lane);
;             float suf[8]; float run = 0.f;
; #pragma unroll
;     ...
; #pragma unroll
	v_pk_add_f32 v[62:63], v[118:119], v[112:113]
	v_pk_mul_f32 v[118:119], v[48:49], s[28:29] op_sel_hi:[1,0]
	v_cmp_lt_i32_e32 vcc, v124, v102
	v_mul_f32_e64 v130, |v118|, s31
	v_exp_f32_e32 v130, v130
	v_mul_f32_e64 v155, |v119|, s31
	v_exp_f32_e32 v155, v155
	v_max_f32_e32 v118, 0, v118
	v_add_f32_e32 v130, 1.0, v130
	v_log_f32_e32 v160, v130
	v_add_f32_e32 v130, 1.0, v155
	v_log_f32_e32 v161, v130
	v_max_f32_e32 v119, 0, v119
	v_pk_add_f32 v[158:159], v[62:63], v[62:63] op_sel:[0,1] op_sel_hi:[1,0]
	v_mov_b32_e32 v120, v88
	v_pk_fma_f32 v[160:161], v[160:161], s[30:31], v[118:119] op_sel_hi:[1,0,1]
	v_or_b32_e32 v63, 42, v157
	v_or_b32_e32 v128, 32, v157
	v_pk_fma_f32 v[48:49], v[48:49], s[28:29], v[160:161] op_sel_hi:[1,0,1] neg_lo:[0,0,1] neg_hi:[0,0,1]
	v_cndmask_b32_e32 v118, 0, v161, vcc
	v_mov_b32_e32 v161, v116
	v_pk_add_f32 v[120:121], v[120:121], v[160:161]
	v_cndmask_b32_e32 v155, v144, v49, vcc
	v_cmp_lt_i32_e32 vcc, v128, v102
	v_cmp_lt_i32_e64 s[6:7], v63, v91
	v_fma_f32 v54, v54, s28, -v121
	v_cndmask_b32_e32 v156, v144, v48, vcc
	v_cndmask_b32_e64 v49, 0, v121, s[6:7]
	v_cndmask_b32_e32 v48, 0, v120, vcc
	v_pk_mul_f32 v[120:121], v[50:51], s[28:29] op_sel_hi:[1,0]
	v_cndmask_b32_e64 v63, v144, v54, s[6:7]
	v_mul_f32_e64 v116, |v120|, s31
	v_mul_f32_e64 v54, |v121|, s31
	v_exp_f32_e32 v116, v116
	v_exp_f32_e32 v54, v54
	v_max_f32_e32 v128, 0, v120
	v_max_f32_e32 v161, 0, v121
	v_add_f32_e32 v116, 1.0, v116
	v_add_f32_e32 v54, 1.0, v54
	v_log_f32_e32 v130, v116
	v_log_f32_e32 v54, v54
	v_cmp_lt_i32_e32 vcc, v126, v102
	v_or_b32_e32 v162, 34, v157
	v_pk_fma_f32 v[128:129], v[130:131], s[30:31], v[128:129] op_sel_hi:[1,0,1]
	v_fmac_f32_e32 v161, 0x3f317218, v54
	v_mov_b32_e32 v160, v128
	v_cndmask_b32_e32 v120, 0, v161, vcc
	v_pk_fma_f32 v[130:131], v[50:51], s[28:29], v[160:161] op_sel_hi:[1,0,1] neg_lo:[0,0,1] neg_hi:[0,0,1]
	v_pk_mul_f32 v[160:161], v[52:53], s[28:29] op_sel_hi:[1,0]
	v_cmp_lt_i32_e64 s[6:7], v162, v102
	v_mul_f32_e64 v50, |v160|, s31
	v_exp_f32_e32 v50, v50
	v_mul_f32_e64 v51, |v161|, s31
	v_exp_f32_e32 v54, v51
	v_max_f32_e32 v160, 0, v160
	v_add_f32_e32 v50, 1.0, v50
	v_log_f32_e32 v162, v50
	v_add_f32_e32 v50, 1.0, v54
	v_log_f32_e32 v163, v50
	v_max_f32_e32 v161, 0, v161
	v_or_b32_e32 v116, 41, v157
	v_or_b32_e32 v119, 40, v157
	v_pk_fma_f32 v[160:161], v[162:163], s[30:31], v[160:161] op_sel_hi:[1,0,1]
	v_cndmask_b32_e64 v172, v144, v130, s[6:7]
	v_cndmask_b32_e64 v50, 0, v128, s[6:7]
	v_add_f32_e32 v54, 0, v160
	v_cmp_lt_i32_e64 s[6:7], v116, v91
	v_cmp_lt_i32_e64 s[10:11], v119, v102
	v_or_b32_e32 v159, 43, v157
	v_cndmask_b32_e64 v173, 0, v161, s[6:7]
	v_cndmask_b32_e64 v54, 0, v54, s[10:11]
	v_cmp_lt_i32_e64 s[8:9], v159, v91
	v_add_f32_e32 v119, v173, v54
	v_pk_add_f32 v[162:163], v[48:49], v[118:119]
	v_cndmask_b32_e64 v51, 0, v129, s[8:9]
	v_pk_add_f32 v[162:163], v[50:51], v[162:163]
	ds_bpermute_b32 v121, v136, v163
	v_fma_f32 v48, v55, s28, -v129
	v_pk_fma_f32 v[52:53], v[52:53], s[28:29], v[160:161] op_sel_hi:[1,0,1] neg_lo:[0,0,1] neg_hi:[0,0,1]
	v_mov_b32_e32 v55, v158
	v_cndmask_b32_e64 v175, v144, v52, s[10:11]
	s_waitcnt lgkmcnt(0)
	v_pk_add_f32 v[128:129], v[120:121], v[162:163]
	ds_bpermute_b32 v54, v136, v128
	v_cndmask_b32_e64 v176, v144, v53, s[6:7]
	v_cndmask_b32_e32 v119, v144, v131, vcc
	v_add_f32_e32 v174, v103, v158
	v_or_b32_e32 v124, 24, v157
	s_waitcnt lgkmcnt(0)
	v_pk_add_f32 v[52:53], v[128:129], v[54:55]
	v_pk_mul_f32 v[128:129], v[44:45], s[28:29] op_sel_hi:[1,0]
	v_pk_add_f32 v[130:131], v[52:53], v[52:53] op_sel:[0,1] op_sel_hi:[1,0]
	v_mul_f32_e64 v55, |v128|, s31
	v_exp_f32_e32 v55, v55
	v_mul_f32_e64 v116, |v129|, s31
	v_exp_f32_e32 v116, v116
	v_max_f32_e32 v128, 0, v128
	v_add_f32_e32 v52, 1.0, v55
	v_log_f32_e32 v158, v52
	v_add_f32_e32 v52, 1.0, v116
	v_log_f32_e32 v159, v52
	v_max_f32_e32 v129, 0, v129
	v_or_b32_e32 v116, 25, v157
	v_cmp_lt_i32_e32 vcc, v116, v91
	v_pk_fma_f32 v[128:129], v[158:159], s[30:31], v[128:129] op_sel_hi:[1,0,1]
	v_cmp_lt_i32_e64 s[6:7], v124, v102
	v_add_f32_e32 v55, 0, v128
	v_pk_fma_f32 v[44:45], v[44:45], s[28:29], v[128:129] op_sel_hi:[1,0,1] neg_lo:[0,0,1] neg_hi:[0,0,1]
	v_cndmask_b32_e32 v177, 0, v129, vcc
	v_pk_mul_f32 v[128:129], v[42:43], s[28:29] op_sel_hi:[1,0]
	v_cndmask_b32_e32 v178, v144, v45, vcc
	v_mul_f32_e64 v45, |v128|, s31
	v_exp_f32_e32 v116, v45
	v_mul_f32_e64 v45, |v129|, s31
	v_exp_f32_e32 v124, v45
	v_cndmask_b32_e64 v55, 0, v55, s[6:7]
	v_cndmask_b32_e64 v179, v144, v44, s[6:7]
	v_add_f32_e32 v44, 1.0, v116
	v_add_f32_e32 v45, v177, v55
	v_add_f32_e32 v55, 1.0, v124
	v_log_f32_e32 v126, v44
	v_log_f32_e32 v55, v55
	v_max_f32_e32 v124, 0, v128
	v_max_f32_e32 v129, 0, v129
	v_pk_fma_f32 v[124:125], v[126:127], s[30:31], v[124:125] op_sel_hi:[1,0,1]
	v_fmac_f32_e32 v129, 0x3f317218, v55
	v_mov_b32_e32 v128, v124
	v_pk_mul_f32 v[158:159], v[40:41], s[28:29] op_sel_hi:[1,0]
	v_pk_fma_f32 v[126:127], v[42:43], s[28:29], v[128:129] op_sel_hi:[1,0,1] neg_lo:[0,0,1] neg_hi:[0,0,1]
	v_mul_f32_e64 v42, |v158|, s31
	v_exp_f32_e32 v42, v42
	v_mul_f32_e64 v43, |v159|, s31
	v_exp_f32_e32 v44, v43
	v_or_b32_e32 v171, 18, v157
	v_add_f32_e32 v42, 1.0, v42
	v_log_f32_e32 v160, v42
	v_add_f32_e32 v42, 1.0, v44
	v_log_f32_e32 v161, v42
	v_cmp_lt_i32_e32 vcc, v171, v102
	v_max_f32_e32 v158, 0, v158
	v_max_f32_e32 v159, 0, v159
	v_cndmask_b32_e32 v55, v144, v126, vcc
	v_cndmask_b32_e32 v42, 0, v124, vcc
	v_pk_fma_f32 v[158:159], v[160:161], s[30:31], v[158:159] op_sel_hi:[1,0,1]
	v_cmp_lt_i32_e32 vcc, v166, v102
	v_mov_b32_e32 v122, v88
	v_or_b32_e32 v168, 26, v157
	v_or_b32_e32 v169, 16, v157
	v_pk_fma_f32 v[160:161], v[40:41], s[28:29], v[158:159] op_sel_hi:[1,0,1] neg_lo:[0,0,1] neg_hi:[0,0,1]
	v_cndmask_b32_e32 v44, 0, v159, vcc
	v_mov_b32_e32 v159, v114
	v_or_b32_e32 v170, 27, v157
	v_cndmask_b32_e64 v48, v144, v48, s[8:9]
	v_pk_add_f32 v[122:123], v[122:123], v[158:159]
	v_cmp_lt_i32_e64 s[8:9], v169, v102
	v_cmp_lt_i32_e64 s[10:11], v168, v91
	v_cmp_lt_i32_e64 s[6:7], v170, v91
	v_cndmask_b32_e64 v40, 0, v122, s[8:9]
	v_cndmask_b32_e64 v41, 0, v123, s[10:11]
	v_cndmask_b32_e64 v43, 0, v125, s[6:7]
	v_pk_add_f32 v[158:159], v[40:41], v[44:45]
	v_cndmask_b32_e64 v160, v144, v160, s[8:9]
	v_pk_add_f32 v[158:159], v[42:43], v[158:159]
	ds_bpermute_b32 v163, v136, v159
	v_cmp_lt_i32_e64 s[8:9], v167, v102
	v_fma_f32 v40, v47, s28, -v125
	v_fma_f32 v46, v46, s28, -v123
	v_cndmask_b32_e64 v162, 0, v129, s[8:9]
	s_waitcnt lgkmcnt(0)
; DEV float shx(float v, int m, int lane) { return __builtin_bit_cast(float, __builtin_amdgcn_ds_bpermute((lane ^ m) << 2, __builtin_bit_cast(int, v))); }
; DEV float fexp2(float x) { return __builtin_amdgcn_exp2f(x); }
; DEV void sb_pass(LAS unsigned char* lds, int tid, int r, int h, int w, const bf16* Kp, size_t kpitch, const bf16* VTp, size_t vpitch, int t_hi, const bf16x8 (&qf)[4], int hi_lim, f32x16 (&o)[2]) {
;     ...
; #pragma unroll
;             for (int o8 = 0; o8 < 8; ++o8) Gp[o8] = shx(G[o8], 32, lane);
;             float suf[8]; float run = 0.f;
; #pragma unroll
;     ...
; #pragma unroll
;             for (int b2 = 0; b2 < 2; ++b2)
; #pragma unroll
;                 for (int g = 0; g < 4; ++g) {
;                     const int o8 = 4 * b2 + g; float after = Rr + suf[o8] + (h == 0 ? Gp[o8] : 0.f);
; #pragma unroll
;                     for (int i = 3; i >= 0; --i) { const float ls = st[b2][4 * g + i];
;                         const float wgt = (ls > -1e29f) ? fexp2((ls - after) * LOG2E) : 0.f;
;                         after += spv[b2][4 * g + i]; st[b2][4 * g + i] = wgt; }
;                 }
;             Rr += run;
	v_pk_add_f32 v[124:125], v[162:163], v[158:159]
	ds_bpermute_b32 v122, v136, v124
	v_mov_b32_e32 v123, v130
	v_cndmask_b32_e64 v166, v144, v46, s[10:11]
	v_cndmask_b32_e64 v45, v144, v127, s[8:9]
	v_cndmask_b32_e32 v161, v144, v161, vcc
	s_waitcnt lgkmcnt(0)
	v_cndmask_b32_e64 v167, 0, v122, s[0:1]
	v_pk_add_f32 v[46:47], v[124:125], v[122:123]
	v_pk_mul_f32 v[122:123], v[36:37], s[28:29] op_sel_hi:[1,0]
	v_pk_add_f32 v[124:125], v[46:47], v[46:47] op_sel:[0,1] op_sel_hi:[1,0]
	v_mul_f32_e64 v114, |v122|, s31
	v_exp_f32_e32 v114, v114
	v_mul_f32_e64 v116, |v123|, s31
	v_exp_f32_e32 v116, v116
	v_max_f32_e32 v122, 0, v122
	v_add_f32_e32 v46, 1.0, v114
	v_log_f32_e32 v126, v46
	v_add_f32_e32 v46, 1.0, v116
	v_log_f32_e32 v127, v46
	v_max_f32_e32 v123, 0, v123
	v_or_b32_e32 v116, 9, v157
	v_cmp_lt_i32_e32 vcc, v116, v91
	v_pk_fma_f32 v[122:123], v[126:127], s[30:31], v[122:123] op_sel_hi:[1,0,1]
	v_cndmask_b32_e64 v40, v144, v40, s[6:7]
	v_add_f32_e32 v114, 0, v122
	v_pk_fma_f32 v[36:37], v[36:37], s[28:29], v[122:123] op_sel_hi:[1,0,1] neg_lo:[0,0,1] neg_hi:[0,0,1]
	v_or_b32_e32 v122, 8, v157
	v_cndmask_b32_e32 v125, 0, v123, vcc
	v_cmp_lt_i32_e64 s[6:7], v122, v102
	v_pk_mul_f32 v[122:123], v[34:35], s[28:29] op_sel_hi:[1,0]
	v_cndmask_b32_e32 v168, v144, v37, vcc
	v_mul_f32_e64 v37, |v122|, s31
	v_exp_f32_e32 v116, v37
	v_mul_f32_e64 v37, |v123|, s31
	v_exp_f32_e32 v126, v37
	v_cndmask_b32_e64 v114, 0, v114, s[6:7]
	v_cndmask_b32_e64 v169, v144, v36, s[6:7]
	v_add_f32_e32 v36, 1.0, v116
	v_add_f32_e32 v37, v125, v114
	v_add_f32_e32 v114, 1.0, v126
	v_log_f32_e32 v116, v36
	v_log_f32_e32 v126, v114
	v_max_f32_e32 v114, 0, v122
	v_max_f32_e32 v123, 0, v123
	v_pk_fma_f32 v[114:115], v[116:117], s[30:31], v[114:115] op_sel_hi:[1,0,1]
	v_or_b32_e32 v165, 2, v157
	v_fmac_f32_e32 v123, 0x3f317218, v126
	v_mov_b32_e32 v122, v114
	v_pk_fma_f32 v[34:35], v[34:35], s[28:29], v[122:123] op_sel_hi:[1,0,1] neg_lo:[0,0,1] neg_hi:[0,0,1]
	v_cmp_lt_i32_e32 vcc, v165, v102
	v_pk_mul_f32 v[116:117], v[32:33], s[28:29] op_sel_hi:[1,0]
	v_or_b32_e32 v164, 11, v157
	v_cndmask_b32_e32 v122, v144, v34, vcc
	v_mul_f32_e64 v34, |v116|, s31
	v_exp_f32_e32 v34, v34
	v_mul_f32_e64 v36, |v117|, s31
	v_exp_f32_e32 v36, v36
	v_max_f32_e32 v116, 0, v116
	v_add_f32_e32 v34, 1.0, v34
	v_log_f32_e32 v128, v34
	v_add_f32_e32 v34, 1.0, v36
	v_log_f32_e32 v129, v34
	v_max_f32_e32 v117, 0, v117
	v_cndmask_b32_e32 v126, 0, v114, vcc
	v_cmp_lt_i32_e32 vcc, v157, v101
	v_pk_fma_f32 v[116:117], v[128:129], s[30:31], v[116:117] op_sel_hi:[1,0,1]
	v_cmp_lt_i32_e64 s[8:9], v157, v102
	v_pk_fma_f32 v[32:33], v[32:33], s[28:29], v[116:117] op_sel_hi:[1,0,1] neg_lo:[0,0,1] neg_hi:[0,0,1]
	v_cndmask_b32_e32 v36, 0, v117, vcc
	v_mov_b32_e32 v117, v152
	v_pk_add_f32 v[116:117], v[88:89], v[116:117]
	v_cmp_lt_i32_e64 s[10:11], v154, v91
	v_cmp_lt_i32_e64 s[6:7], v164, v91
	v_cndmask_b32_e64 v128, 0, v116, s[8:9]
	v_cndmask_b32_e64 v129, 0, v117, s[10:11]
	v_add_f32_e32 v52, v103, v130
	v_cndmask_b32_e64 v127, 0, v115, s[6:7]
	v_pk_add_f32 v[130:131], v[128:129], v[36:37]
	v_cndmask_b32_e64 v114, v144, v32, s[8:9]
	v_pk_add_f32 v[130:131], v[126:127], v[130:131]
	ds_bpermute_b32 v159, v136, v131
	v_cmp_lt_i32_e64 s[8:9], v153, v102
	v_cndmask_b32_e32 v89, v144, v33, vcc
	v_fma_f32 v33, v38, s28, -v117
	v_cndmask_b32_e64 v158, 0, v123, s[8:9]
	v_cndmask_b32_e64 v37, v144, v35, s[8:9]
	s_waitcnt lgkmcnt(0)
	v_pk_add_f32 v[34:35], v[158:159], v[130:131]
	ds_bpermute_b32 v32, v136, v34
	v_cndmask_b32_e64 v38, v144, v33, s[10:11]
	v_mov_b32_e32 v33, v124
	v_fma_f32 v39, v39, s28, -v115
	v_cmp_lt_f32_e32 vcc, s33, v37
	s_waitcnt lgkmcnt(0)
	v_cndmask_b32_e64 v115, 0, v32, s[0:1]
	v_pk_add_f32 v[32:33], v[34:35], v[32:33]
	v_add_f32_e32 v46, v103, v124
	v_add_f32_e32 v34, v103, v33
	v_add_f32_e32 v34, v115, v34
	v_sub_f32_e32 v35, v37, v34
	v_add_f32_e32 v34, v158, v34
	v_mul_f32_e32 v35, 0x3fb8aa3b, v35
	v_sub_f32_e32 v115, v122, v34
	v_exp_f32_e32 v35, v35
	v_mul_f32_e32 v115, 0x3fb8aa3b, v115
	v_exp_f32_e32 v115, v115
	v_add_f32_e32 v34, v126, v34
	v_cndmask_b32_e32 v35, 0, v35, vcc
	v_cmp_lt_f32_e32 vcc, s33, v122
	v_cndmask_b32_e64 v116, 0, v159, s[0:1]
	v_cndmask_b32_e64 v39, v144, v39, s[6:7]
	v_cndmask_b32_e32 v37, 0, v115, vcc
	v_sub_f32_e32 v115, v89, v34
	v_mul_f32_e32 v115, 0x3fb8aa3b, v115
	v_exp_f32_e32 v115, v115
	v_add_f32_e32 v34, v36, v34
	v_sub_f32_e32 v34, v114, v34
	v_add_f32_e32 v46, v116, v46
	v_mul_f32_e32 v34, 0x3fb8aa3b, v34
	v_cmp_lt_f32_e32 vcc, s33, v89
	v_sub_f32_e32 v89, v39, v46
	v_exp_f32_e32 v34, v34
	v_mul_f32_e32 v89, 0x3fb8aa3b, v89
	v_add_f32_e32 v46, v127, v46
	v_cndmask_b32_e32 v36, 0, v115, vcc
	v_cmp_lt_f32_e32 vcc, s33, v114
	v_exp_f32_e32 v89, v89
	v_sub_f32_e32 v114, v38, v46
	v_mul_f32_e32 v114, 0x3fb8aa3b, v114
	v_exp_f32_e32 v114, v114
	v_cndmask_b32_e32 v34, 0, v34, vcc
	v_cmp_lt_f32_e32 vcc, s33, v39
	v_add_f32_e32 v46, v129, v46
	v_add_f32_e32 v47, v103, v47
	v_cndmask_b32_e32 v39, 0, v89, vcc
	v_sub_f32_e32 v89, v168, v46
	v_add_f32_e32 v46, v125, v46
	v_cmp_lt_f32_e32 vcc, s33, v38
	v_mul_f32_e32 v89, 0x3fb8aa3b, v89
	v_sub_f32_e32 v46, v169, v46
	v_add_f32_e32 v47, v167, v47
	v_cndmask_b32_e32 v38, 0, v114, vcc
	v_exp_f32_e32 v89, v89
	v_mul_f32_e32 v46, 0x3fb8aa3b, v46
	v_sub_f32_e32 v114, v45, v47
	v_add_f32_e32 v47, v162, v47
	v_exp_f32_e32 v46, v46
	v_mul_f32_e32 v114, 0x3fb8aa3b, v114
	v_sub_f32_e32 v115, v55, v47
	v_add_f32_e32 v42, v42, v47
	v_exp_f32_e32 v114, v114
	v_mul_f32_e32 v115, 0x3fb8aa3b, v115
	v_sub_f32_e32 v47, v161, v42
	v_cmp_lt_f32_e32 vcc, s33, v168
	v_exp_f32_e32 v115, v115
	v_mul_f32_e32 v47, 0x3fb8aa3b, v47
; #define LAS __attribute__((address_space(3)))
; #define MFMA32(a, b, c) __builtin_amdgcn_mfma_f32_32x32x16_bf16((a), (b), (c), 0, 0, 0)
; DEV unsigned pk2(float lo, float hi) { f32x2_ v; v.x = lo; v.y = hi; return __builtin_bit_cast(unsigned, __builtin_convertvector(v, bf16x2_)); }
; DEV float fexp2(float x) { return __builtin_amdgcn_exp2f(x); }
; DEV void pack_p(bf16x8 (&pf)[4], const f32x16 (&st)[2]) {
; #pragma unroll
;     for (int b2 = 0; b2 < 2; ++b2)
; #pragma unroll
;         for (int s = 0; s < 2; ++s) { u32x4 p; p.x = pk2(st[b2][8 * s], st[b2][8 * s + 1]); p.y = pk2(st[b2][8 * s + 2], st[b2][8 * s + 3]);
;             p.z = pk2(st[b2][8 * s + 4], st[b2][8 * s + 5]); p.w = pk2(st[b2][8 * s + 6], st[b2][8 * s + 7]); pf[2 * b2 + s] = __builtin_bit_cast(bf16x8, p); }
; }
; DEV void pv_load(bf16x8 (&vf)[2][4], const LAS unsigned char* vb, int r, int h) {
; #pragma unroll
;     for (int db = 0; db < 2; ++db)
; #pragma unroll
;         for (int f = 0; f < 4; ++f) { const LAS unsigned char* p = vb + (32 * db + r) * 136 + (16 * f + 4 * h) * 2;
;             const s16x4 lo = *(const LAS s16x4*)p, hi = *(const LAS s16x4*)(p + 16);
;             vf[db][f] = __builtin_shufflevector(lo, hi, 0, 1, 2, 3, 4, 5, 6, 7); }
;     __builtin_amdgcn_sched_barrier(0);
; }
; DEV void pv_mma(f32x16 (&o)[2], const bf16x8 (&vf)[2][4], const bf16x8 (&pf)[4]) {
;     __builtin_amdgcn_sched_barrier(0);
; #pragma unroll
;     for (int f = 0; f < 4; ++f)
; #pragma unroll
;         for (int db = 0; db < 2; ++db) o[db] = MFMA32(vf[db][f], pf[f], o[db]);
;     __builtin_amdgcn_sched_barrier(0);
; }
; DEV void sb_pass(LAS unsigned char* lds, int tid, int r, int h, int w, const bf16* Kp, size_t kpitch, const bf16* VTp, size_t vpitch, int t_hi, const bf16x8 (&qf)[4], int hi_lim, f32x16 (&o)[2]) {
;     ...
;                     const int o8 = 4 * b2 + g; float after = Rr + suf[o8] + (h == 0 ? Gp[o8] : 0.f);
; #pragma unroll
;                     for (int i = 3; i >= 0; --i) { const float ls = st[b2][4 * g + i];
;                         const float wgt = (ls > -1e29f) ? fexp2((ls - after) * LOG2E) : 0.f;
;                         after += spv[b2][4 * g + i]; st[b2][4 * g + i] = wgt; }
;                 }
;             Rr += run;
;             bf16x8 pf[4]; pack_p(pf, st);
;             pv_tile(o, vb, pf, r, h);
	v_cndmask_b32_e32 v89, 0, v89, vcc
	v_cmp_lt_f32_e32 vcc, s33, v169
	v_exp_f32_e32 v47, v47
	v_cndmask_b32_e64 v163, 0, v163, s[0:1]
	v_cndmask_b32_e32 v46, 0, v46, vcc
	v_cmp_lt_f32_e32 vcc, s33, v45
	v_add_f32_e32 v42, v44, v42
	v_sub_f32_e32 v42, v160, v42
	v_cndmask_b32_e32 v45, 0, v114, vcc
	v_cmp_lt_f32_e32 vcc, s33, v55
	v_mul_f32_e32 v42, 0x3fb8aa3b, v42
	v_exp_f32_e32 v42, v42
	v_cndmask_b32_e32 v55, 0, v115, vcc
	v_cmp_lt_f32_e32 vcc, s33, v161
	v_cndmask_b32_e64 v114, 0, v121, s[0:1]
	v_add_f32_e32 v114, v114, v174
	v_cndmask_b32_e32 v44, 0, v47, vcc
	v_add_f32_e32 v47, v163, v52
	v_sub_f32_e32 v52, v40, v47
	v_mul_f32_e32 v52, 0x3fb8aa3b, v52
	v_exp_f32_e32 v52, v52
	v_cmp_lt_f32_e32 vcc, s33, v160
	v_add_f32_e32 v43, v43, v47
	v_sub_f32_e32 v47, v166, v43
	v_cndmask_b32_e32 v42, 0, v42, vcc
	v_cmp_lt_f32_e32 vcc, s33, v40
	v_add_f32_e32 v41, v41, v43
	v_mul_f32_e32 v47, 0x3fb8aa3b, v47
	v_cndmask_b32_e32 v40, 0, v52, vcc
	v_sub_f32_e32 v43, v178, v41
	v_add_f32_e32 v41, v177, v41
	v_add_f32_e32 v52, v103, v53
	v_cndmask_b32_e64 v53, 0, v54, s[0:1]
	v_exp_f32_e32 v47, v47
	v_mul_f32_e32 v43, 0x3fb8aa3b, v43
	v_sub_f32_e32 v41, v179, v41
	v_add_f32_e32 v52, v53, v52
	v_exp_f32_e32 v43, v43
	v_mul_f32_e32 v41, 0x3fb8aa3b, v41
	v_sub_f32_e32 v53, v119, v52
	v_add_f32_e32 v52, v120, v52
	v_exp_f32_e32 v41, v41
	v_mul_f32_e32 v53, 0x3fb8aa3b, v53
	v_sub_f32_e32 v54, v172, v52
	v_add_f32_e32 v50, v50, v52
	v_cmp_lt_f32_e32 vcc, s33, v166
	v_exp_f32_e32 v53, v53
	v_mul_f32_e32 v54, 0x3fb8aa3b, v54
	v_sub_f32_e32 v52, v155, v50
	v_add_f32_e32 v50, v118, v50
	v_cndmask_b32_e32 v47, 0, v47, vcc
	v_cmp_lt_f32_e32 vcc, s33, v178
	v_exp_f32_e32 v54, v54
	v_mul_f32_e32 v52, 0x3fb8aa3b, v52
	v_sub_f32_e32 v50, v156, v50
	v_cndmask_b32_e32 v43, 0, v43, vcc
	v_cmp_lt_f32_e32 vcc, s33, v179
	v_exp_f32_e32 v52, v52
	v_mul_f32_e32 v50, 0x3fb8aa3b, v50
	v_sub_f32_e32 v115, v48, v114
	v_add_f32_e32 v51, v51, v114
	v_cndmask_b32_e32 v41, 0, v41, vcc
	v_cmp_lt_f32_e32 vcc, s33, v119
	v_exp_f32_e32 v50, v50
	v_mul_f32_e32 v115, 0x3fb8aa3b, v115
	v_sub_f32_e32 v114, v63, v51
	v_add_f32_e32 v49, v49, v51
	v_cndmask_b32_e32 v53, 0, v53, vcc
	v_cmp_lt_f32_e32 vcc, s33, v172
	v_exp_f32_e32 v115, v115
	v_mul_f32_e32 v114, 0x3fb8aa3b, v114
	v_sub_f32_e32 v51, v176, v49
	v_add_f32_e32 v49, v173, v49
	v_add_f32_e32 v62, v103, v62
	v_cndmask_b32_e64 v113, 0, v113, s[0:1]
	v_cndmask_b32_e32 v54, 0, v54, vcc
	v_cmp_lt_f32_e32 vcc, s33, v155
	v_exp_f32_e32 v114, v114
	v_mul_f32_e32 v51, 0x3fb8aa3b, v51
	v_sub_f32_e32 v49, v175, v49
	v_add_f32_e32 v62, v113, v62
	v_cndmask_b32_e32 v52, 0, v52, vcc
	v_cmp_lt_f32_e32 vcc, s33, v156
	v_exp_f32_e32 v51, v51
	v_mul_f32_e32 v49, 0x3fb8aa3b, v49
	v_sub_f32_e32 v113, v150, v62
	v_add_f32_e32 v62, v111, v62
	v_cndmask_b32_e32 v50, 0, v50, vcc
	v_cmp_lt_f32_e32 vcc, s33, v48
	v_exp_f32_e32 v49, v49
	v_mul_f32_e32 v113, 0x3fb8aa3b, v113
	v_sub_f32_e32 v111, v149, v62
	v_add_f32_e32 v59, v59, v62
	v_cndmask_b32_e32 v48, 0, v115, vcc
	v_cmp_lt_f32_e32 vcc, s33, v63
	v_exp_f32_e32 v113, v113
	v_mul_f32_e32 v111, 0x3fb8aa3b, v111
	v_sub_f32_e32 v62, v148, v59
	v_add_f32_e32 v59, v61, v59
	v_cndmask_b32_e32 v63, 0, v114, vcc
	v_cmp_lt_f32_e32 vcc, s33, v176
	v_exp_f32_e32 v111, v111
	v_mul_f32_e32 v62, 0x3fb8aa3b, v62
	v_sub_f32_e32 v59, v147, v59
	v_cndmask_b32_e32 v51, 0, v51, vcc
	v_cmp_lt_f32_e32 vcc, s33, v175
	v_exp_f32_e32 v62, v62
	v_mul_f32_e32 v59, 0x3fb8aa3b, v59
	v_cndmask_b32_e32 v49, 0, v49, vcc
	v_cmp_lt_f32_e32 vcc, s33, v150
	v_exp_f32_e32 v59, v59
	v_cndmask_b32_e64 v61, 0, v112, s[0:1]
	v_cndmask_b32_e32 v123, 0, v113, vcc
	v_cmp_lt_f32_e32 vcc, s33, v149
	v_add_f32_e32 v32, v32, v33
	v_cvt_pk_bf16_f32 v33, v37, v35
	v_cndmask_b32_e32 v124, 0, v111, vcc
	v_cmp_lt_f32_e32 vcc, s33, v148
	v_cvt_pk_bf16_f32 v35, v38, v39
	v_cvt_pk_bf16_f32 v37, v55, v45
	v_cndmask_b32_e32 v122, 0, v62, vcc
	v_cmp_lt_f32_e32 vcc, s33, v147
	v_cvt_pk_bf16_f32 v38, v41, v43
	v_cvt_pk_bf16_f32 v39, v47, v40
	v_cndmask_b32_e32 v125, 0, v59, vcc
	v_add_f32_e32 v59, 0, v103
	v_add_f32_e32 v59, v59, v61
	v_sub_f32_e32 v61, v151, v59
	v_add_f32_e32 v59, v110, v59
	v_mul_f32_e32 v61, 0x3fb8aa3b, v61
	v_sub_f32_e32 v62, v60, v59
	v_add_f32_e32 v58, v58, v59
	v_exp_f32_e32 v61, v61
	v_mul_f32_e32 v62, 0x3fb8aa3b, v62
	v_sub_f32_e32 v59, v57, v58
	v_add_f32_e32 v56, v56, v58
	v_exp_f32_e32 v62, v62
	v_mul_f32_e32 v59, 0x3fb8aa3b, v59
	v_sub_f32_e32 v56, v145, v56
	v_exp_f32_e32 v59, v59
	v_mul_f32_e32 v56, 0x3fb8aa3b, v56
	v_cmp_lt_f32_e32 vcc, s33, v151
	v_exp_f32_e32 v56, v56
	v_add_f32_e32 v103, v103, v32
	v_cndmask_b32_e32 v126, 0, v61, vcc
	v_cmp_lt_f32_e32 vcc, s33, v60
	v_add_u32_e32 v60, s45, v137
	v_cvt_pk_bf16_f32 v32, v34, v36
	v_cndmask_b32_e32 v127, 0, v62, vcc
	v_cmp_lt_f32_e32 vcc, s33, v57
	v_cvt_pk_bf16_f32 v34, v46, v89
	v_add_u32_e32 v89, 0x1000, v60
	v_cndmask_b32_e32 v128, 0, v59, vcc
	v_cmp_lt_f32_e32 vcc, s33, v145
	v_cvt_pk_bf16_f32 v36, v42, v44
	v_cvt_pk_bf16_f32 v40, v50, v52
	v_cndmask_b32_e32 v129, 0, v56, vcc
	v_cvt_pk_bf16_f32 v41, v54, v53
	v_cvt_pk_bf16_f32 v42, v49, v51
	v_cvt_pk_bf16_f32 v43, v63, v48
	ds_read2_b64 v[44:47], v60 offset1:2
	ds_read2_b64 v[48:51], v60 offset0:4 offset1:6
	ds_read2_b64 v[52:55], v60 offset0:8 offset1:10
	ds_read2_b64 v[56:59], v60 offset0:12 offset1:14
	ds_read2_b64 v[60:63], v89 offset0:32 offset1:34
	ds_read2_b64 v[110:113], v89 offset0:36 offset1:38
	ds_read2_b64 v[114:117], v89 offset0:40 offset1:42
	ds_read2_b64 v[118:121], v89 offset0:44 offset1:46
	v_cvt_pk_bf16_f32 v122, v125, v122
	v_cvt_pk_bf16_f32 v123, v124, v123
	v_cvt_pk_bf16_f32 v124, v129, v128
	v_cvt_pk_bf16_f32 v125, v127, v126
	s_setprio 1
	s_waitcnt lgkmcnt(7)
	v_mfma_f32_32x32x16_bf16 v[16:31], v[44:47], v[32:35], v[16:31]
	s_waitcnt lgkmcnt(3)
	v_mfma_f32_32x32x16_bf16 v[0:15], v[60:63], v[32:35], v[0:15]
	v_mfma_f32_32x32x16_bf16 v[16:31], v[48:51], v[36:39], v[16:31]
	s_waitcnt lgkmcnt(2)
	v_mfma_f32_32x32x16_bf16 v[0:15], v[110:113], v[36:39], v[0:15]
	v_mfma_f32_32x32x16_bf16 v[16:31], v[52:55], v[40:43], v[16:31]
	s_waitcnt lgkmcnt(1)
	v_mfma_f32_32x32x16_bf16 v[0:15], v[114:117], v[40:43], v[0:15]
	v_mfma_f32_32x32x16_bf16 v[16:31], v[56:59], v[122:125], v[16:31]
	s_waitcnt lgkmcnt(0)
	v_mfma_f32_32x32x16_bf16 v[0:15], v[118:121], v[122:125], v[0:15]
	s_setprio 0

;     __device__ __forceinline__ void operator()(const f32x4 (&acc)[2][2][4][2], const Unit& u, int wr, int wc, int fr, int fq) const {
;     ...
;         for (int ai = 0; ai < 2; ++ai)
; #pragma unroll
;             for (int m = 0; m < 4; ++m) { const int row = u.pm * BM + ai * HALF + wr * 64 + m * 16 + fr; const size_t off = (size_t)row * ldc + col0;
;                 float mean = 0.f, rstd = 1.f;
;                 if (g) { mean = stats[2 * row]; rstd = stats[2 * row + 1]; }
; #pragma unroll
;                 for (int bj = 0; bj < 2; ++bj)
; #pragma unroll
;                     for (int n = 0; n < 2; ++n) { const size_t c = off + bj * HALF + n * 16; f32x4 bb = *(const f32x4*)(base + c);
;                         if (g) bb = (bb - mean) * rstd * gv[bj][n] + bv[bj][n];
;                         *(f32x4*)(out + c) = bb * alpha + acc[ai][bj][m][n]; }
;                 if (m & 1) asm volatile("" ::: "memory"); }
.LBB0_262:
	v_mov_b32_e32 v140, v144
	v_mov_b32_e32 v142, v145
	s_lshl_b32 s27, s61, 8
	s_or_b32 s27, s27, s46
	v_lshl_add_u32 v140, v140, 2, s27
	s_lshl_b32 s27, s36, 8
	s_add_i32 s27, s27, s45
	v_add_u32_e32 v142, s27, v142
	v_ashrrev_i32_e32 v143, 31, v142
	v_ashrrev_i32_e32 v141, 31, v140
	s_andn2_b64 vcc, exec, s[0:1]
	s_mov_b64 s[0:1], -1
	v_lshl_add_u32 v206, v142, 10, v140
	v_lshlrev_b32_e32 v206, 2, v206
	v_add_u32_e32 v207, 16, v142
	v_lshl_add_u32 v207, v207, 10, v140
	v_lshlrev_b32_e32 v207, 2, v207
	v_add_u32_e32 v208, 32, v142
	v_lshl_add_u32 v208, v208, 10, v140
	v_lshlrev_b32_e32 v208, 2, v208
	v_add_u32_e32 v209, 48, v142
	v_lshl_add_u32 v209, v209, 10, v140
	v_lshlrev_b32_e32 v209, 2, v209
	v_add_u32_e32 v210, 128, v142
	v_lshl_add_u32 v210, v210, 10, v140
	v_lshlrev_b32_e32 v210, 2, v210
	v_add_u32_e32 v211, 144, v142
	v_lshl_add_u32 v211, v211, 10, v140
	v_lshlrev_b32_e32 v211, 2, v211
	v_add_u32_e32 v212, 160, v142
	v_lshl_add_u32 v212, v212, 10, v140
	v_lshlrev_b32_e32 v212, 2, v212
	v_add_u32_e32 v213, 176, v142
	v_lshl_add_u32 v213, v213, 10, v140
	v_lshlrev_b32_e32 v213, 2, v213
	global_load_dwordx4 v[152:155], v206, s[6:7]
	global_load_dwordx4 v[156:159], v206, s[6:7] offset:64
	global_load_dwordx4 v[160:163], v206, s[6:7] offset:512
	global_load_dwordx4 v[164:167], v206, s[6:7] offset:576
	global_load_dwordx4 v[168:171], v207, s[6:7]
	global_load_dwordx4 v[172:175], v207, s[6:7] offset:64
	global_load_dwordx4 v[176:179], v207, s[6:7] offset:512
	global_load_dwordx4 v[180:183], v207, s[6:7] offset:576
	s_waitcnt vmcnt(0)
	v_pk_fma_f32 v[154:155], v[154:155], s[22:23], v[126:127] op_sel_hi:[1,0,1]
	v_pk_fma_f32 v[152:153], v[152:153], s[22:23], v[124:125] op_sel_hi:[1,0,1]
	global_store_dwordx4 v206, v[152:155], s[48:49]
	v_pk_fma_f32 v[158:159], v[158:159], s[22:23], v[122:123] op_sel_hi:[1,0,1]
	v_pk_fma_f32 v[156:157], v[156:157], s[22:23], v[120:121] op_sel_hi:[1,0,1]
	global_store_dwordx4 v206, v[156:159], s[48:49] offset:64
	v_pk_fma_f32 v[162:163], v[162:163], s[22:23], v[118:119] op_sel_hi:[1,0,1]
	v_pk_fma_f32 v[160:161], v[160:161], s[22:23], v[116:117] op_sel_hi:[1,0,1]
	global_store_dwordx4 v206, v[160:163], s[48:49] offset:512
	v_pk_fma_f32 v[166:167], v[166:167], s[22:23], v[106:107] op_sel_hi:[1,0,1]
	v_pk_fma_f32 v[164:165], v[164:165], s[22:23], v[104:105] op_sel_hi:[1,0,1]
	global_store_dwordx4 v206, v[164:167], s[48:49] offset:576
	v_pk_fma_f32 v[170:171], v[170:171], s[22:23], v[114:115] op_sel_hi:[1,0,1]
	v_pk_fma_f32 v[168:169], v[168:169], s[22:23], v[112:113] op_sel_hi:[1,0,1]
	global_store_dwordx4 v207, v[168:171], s[48:49]
	v_pk_fma_f32 v[174:175], v[174:175], s[22:23], v[110:111] op_sel_hi:[1,0,1]
	v_pk_fma_f32 v[172:173], v[172:173], s[22:23], v[108:109] op_sel_hi:[1,0,1]
	global_store_dwordx4 v207, v[172:175], s[48:49] offset:64
	v_pk_fma_f32 v[178:179], v[178:179], s[22:23], v[102:103] op_sel_hi:[1,0,1]
	v_pk_fma_f32 v[176:177], v[176:177], s[22:23], v[100:101] op_sel_hi:[1,0,1]
	global_store_dwordx4 v207, v[176:179], s[48:49] offset:512
	v_pk_fma_f32 v[182:183], v[182:183], s[22:23], v[90:91] op_sel_hi:[1,0,1]
	v_pk_fma_f32 v[180:181], v[180:181], s[22:23], v[88:89] op_sel_hi:[1,0,1]
	global_store_dwordx4 v207, v[180:183], s[48:49] offset:576
	global_load_dwordx4 v[152:155], v208, s[6:7]
	global_load_dwordx4 v[156:159], v208, s[6:7] offset:64
	global_load_dwordx4 v[160:163], v208, s[6:7] offset:512
	global_load_dwordx4 v[164:167], v208, s[6:7] offset:576
	global_load_dwordx4 v[168:171], v209, s[6:7]
	global_load_dwordx4 v[172:175], v209, s[6:7] offset:64
	global_load_dwordx4 v[176:179], v209, s[6:7] offset:512
	global_load_dwordx4 v[180:183], v209, s[6:7] offset:576
	s_waitcnt vmcnt(0)
	v_pk_fma_f32 v[154:155], v[154:155], s[22:23], v[98:99] op_sel_hi:[1,0,1]
	v_pk_fma_f32 v[152:153], v[152:153], s[22:23], v[96:97] op_sel_hi:[1,0,1]
	global_store_dwordx4 v208, v[152:155], s[48:49]
	v_pk_fma_f32 v[158:159], v[158:159], s[22:23], v[94:95] op_sel_hi:[1,0,1]
	v_pk_fma_f32 v[156:157], v[156:157], s[22:23], v[92:93] op_sel_hi:[1,0,1]
	global_store_dwordx4 v208, v[156:159], s[48:49] offset:64
	v_pk_fma_f32 v[162:163], v[162:163], s[22:23], v[86:87] op_sel_hi:[1,0,1]
	v_pk_fma_f32 v[160:161], v[160:161], s[22:23], v[84:85] op_sel_hi:[1,0,1]
	global_store_dwordx4 v208, v[160:163], s[48:49] offset:512
	v_pk_fma_f32 v[166:167], v[166:167], s[22:23], v[74:75] op_sel_hi:[1,0,1]
	v_pk_fma_f32 v[164:165], v[164:165], s[22:23], v[72:73] op_sel_hi:[1,0,1]
	global_store_dwordx4 v208, v[164:167], s[48:49] offset:576
	v_pk_fma_f32 v[170:171], v[170:171], s[22:23], v[82:83] op_sel_hi:[1,0,1]
	v_pk_fma_f32 v[168:169], v[168:169], s[22:23], v[80:81] op_sel_hi:[1,0,1]
	global_store_dwordx4 v209, v[168:171], s[48:49]
	v_pk_fma_f32 v[174:175], v[174:175], s[22:23], v[78:79] op_sel_hi:[1,0,1]
	v_pk_fma_f32 v[172:173], v[172:173], s[22:23], v[76:77] op_sel_hi:[1,0,1]
	global_store_dwordx4 v209, v[172:175], s[48:49] offset:64
	v_pk_fma_f32 v[178:179], v[178:179], s[22:23], v[70:71] op_sel_hi:[1,0,1]
	v_pk_fma_f32 v[176:177], v[176:177], s[22:23], v[68:69] op_sel_hi:[1,0,1]
	global_store_dwordx4 v209, v[176:179], s[48:49] offset:512
	v_pk_fma_f32 v[182:183], v[182:183], s[22:23], v[66:67] op_sel_hi:[1,0,1]
	v_pk_fma_f32 v[180:181], v[180:181], s[22:23], v[64:65] op_sel_hi:[1,0,1]
	global_store_dwordx4 v209, v[180:183], s[48:49] offset:576
	global_load_dwordx4 v[152:155], v210, s[6:7]
	global_load_dwordx4 v[156:159], v210, s[6:7] offset:64
	global_load_dwordx4 v[160:163], v210, s[6:7] offset:512
	global_load_dwordx4 v[164:167], v210, s[6:7] offset:576
	global_load_dwordx4 v[168:171], v211, s[6:7]
	global_load_dwordx4 v[172:175], v211, s[6:7] offset:64
	global_load_dwordx4 v[176:179], v211, s[6:7] offset:512
	global_load_dwordx4 v[180:183], v211, s[6:7] offset:576
	s_waitcnt vmcnt(0)
;     __device__ __forceinline__ void operator()(const f32x4 (&acc)[2][2][4][2], const Unit& u, int wr, int wc, int fr, int fq) const {
;     ...
;         for (int ai = 0; ai < 2; ++ai)
; #pragma unroll
;             for (int m = 0; m < 4; ++m) { const int row = u.pm * BM + ai * HALF + wr * 64 + m * 16 + fr; const size_t off = (size_t)row * ldc + col0;
;                 float mean = 0.f, rstd = 1.f;
;                 if (g) { mean = stats[2 * row]; rstd = stats[2 * row + 1]; }
; #pragma unroll
;                 for (int bj = 0; bj < 2; ++bj)
; #pragma unroll
;                     for (int n = 0; n < 2; ++n) { const size_t c = off + bj * HALF + n * 16; f32x4 bb = *(const f32x4*)(base + c);
;                         if (g) bb = (bb - mean) * rstd * gv[bj][n] + bv[bj][n];
;                         *(f32x4*)(out + c) = bb * alpha + acc[ai][bj][m][n]; }
;                 if (m & 1) asm volatile("" ::: "memory"); }
	v_pk_fma_f32 v[154:155], v[154:155], s[22:23], v[62:63] op_sel_hi:[1,0,1]
	v_pk_fma_f32 v[152:153], v[152:153], s[22:23], v[60:61] op_sel_hi:[1,0,1]
	global_store_dwordx4 v210, v[152:155], s[48:49]
	v_pk_fma_f32 v[158:159], v[158:159], s[22:23], v[58:59] op_sel_hi:[1,0,1]
	v_pk_fma_f32 v[156:157], v[156:157], s[22:23], v[56:57] op_sel_hi:[1,0,1]
	global_store_dwordx4 v210, v[156:159], s[48:49] offset:64
	v_pk_fma_f32 v[162:163], v[162:163], s[22:23], v[54:55] op_sel_hi:[1,0,1]
	v_pk_fma_f32 v[160:161], v[160:161], s[22:23], v[52:53] op_sel_hi:[1,0,1]
	global_store_dwordx4 v210, v[160:163], s[48:49] offset:512
	v_pk_fma_f32 v[166:167], v[166:167], s[22:23], v[42:43] op_sel_hi:[1,0,1]
	v_pk_fma_f32 v[164:165], v[164:165], s[22:23], v[40:41] op_sel_hi:[1,0,1]
	global_store_dwordx4 v210, v[164:167], s[48:49] offset:576
	v_pk_fma_f32 v[170:171], v[170:171], s[22:23], v[50:51] op_sel_hi:[1,0,1]
	v_pk_fma_f32 v[168:169], v[168:169], s[22:23], v[48:49] op_sel_hi:[1,0,1]
	global_store_dwordx4 v211, v[168:171], s[48:49]
	v_pk_fma_f32 v[174:175], v[174:175], s[22:23], v[46:47] op_sel_hi:[1,0,1]
	v_pk_fma_f32 v[172:173], v[172:173], s[22:23], v[44:45] op_sel_hi:[1,0,1]
	global_store_dwordx4 v211, v[172:175], s[48:49] offset:64
	v_pk_fma_f32 v[178:179], v[178:179], s[22:23], v[38:39] op_sel_hi:[1,0,1]
	v_pk_fma_f32 v[176:177], v[176:177], s[22:23], v[36:37] op_sel_hi:[1,0,1]
	global_store_dwordx4 v211, v[176:179], s[48:49] offset:512
	v_pk_fma_f32 v[182:183], v[182:183], s[22:23], v[26:27] op_sel_hi:[1,0,1]
	v_pk_fma_f32 v[180:181], v[180:181], s[22:23], v[24:25] op_sel_hi:[1,0,1]
	global_store_dwordx4 v211, v[180:183], s[48:49] offset:576
	global_load_dwordx4 v[152:155], v212, s[6:7]
	global_load_dwordx4 v[156:159], v212, s[6:7] offset:64
	global_load_dwordx4 v[160:163], v212, s[6:7] offset:512
	global_load_dwordx4 v[164:167], v212, s[6:7] offset:576
	global_load_dwordx4 v[168:171], v213, s[6:7]
	global_load_dwordx4 v[172:175], v213, s[6:7] offset:64
	global_load_dwordx4 v[176:179], v213, s[6:7] offset:512
	global_load_dwordx4 v[180:183], v213, s[6:7] offset:576
	s_waitcnt vmcnt(0)
	v_pk_fma_f32 v[154:155], v[154:155], s[22:23], v[34:35] op_sel_hi:[1,0,1]
	v_pk_fma_f32 v[152:153], v[152:153], s[22:23], v[32:33] op_sel_hi:[1,0,1]
	global_store_dwordx4 v212, v[152:155], s[48:49]
	v_pk_fma_f32 v[158:159], v[158:159], s[22:23], v[30:31] op_sel_hi:[1,0,1]
	v_pk_fma_f32 v[156:157], v[156:157], s[22:23], v[28:29] op_sel_hi:[1,0,1]
	global_store_dwordx4 v212, v[156:159], s[48:49] offset:64
	v_pk_fma_f32 v[162:163], v[162:163], s[22:23], v[22:23] op_sel_hi:[1,0,1]
	v_pk_fma_f32 v[160:161], v[160:161], s[22:23], v[20:21] op_sel_hi:[1,0,1]
	global_store_dwordx4 v212, v[160:163], s[48:49] offset:512
	v_pk_fma_f32 v[166:167], v[166:167], s[22:23], v[10:11] op_sel_hi:[1,0,1]
	v_pk_fma_f32 v[164:165], v[164:165], s[22:23], v[8:9] op_sel_hi:[1,0,1]
	global_store_dwordx4 v212, v[164:167], s[48:49] offset:576
	v_pk_fma_f32 v[170:171], v[170:171], s[22:23], v[18:19] op_sel_hi:[1,0,1]
	v_pk_fma_f32 v[168:169], v[168:169], s[22:23], v[16:17] op_sel_hi:[1,0,1]
	global_store_dwordx4 v213, v[168:171], s[48:49]
	v_pk_fma_f32 v[174:175], v[174:175], s[22:23], v[14:15] op_sel_hi:[1,0,1]
	v_pk_fma_f32 v[172:173], v[172:173], s[22:23], v[12:13] op_sel_hi:[1,0,1]
	global_store_dwordx4 v213, v[172:175], s[48:49] offset:64
	v_pk_fma_f32 v[178:179], v[178:179], s[22:23], v[6:7] op_sel_hi:[1,0,1]
	v_pk_fma_f32 v[176:177], v[176:177], s[22:23], v[4:5] op_sel_hi:[1,0,1]
	global_store_dwordx4 v213, v[176:179], s[48:49] offset:512
	v_pk_fma_f32 v[182:183], v[182:183], s[22:23], v[2:3] op_sel_hi:[1,0,1]
	v_pk_fma_f32 v[180:181], v[180:181], s[22:23], v[0:1] op_sel_hi:[1,0,1]
	global_store_dwordx4 v213, v[180:183], s[48:49] offset:576
	s_cbranch_vccnz .LBB0_251
	s_andn2_b64 vcc, exec, s[8:9]
	s_cbranch_vccnz .LBB0_250
	s_barrier
	s_branch .LBB0_250
